# mixer work queue: retention-state units dequeued first (was 8th of 11 types) so their long serial loop no longer forms the phase tail
# speedup vs baseline: 1.0255x; 1.0255x over previous
.LBB0_855:
	v_add_u32_e32 v0, s3, v196
	v_and_b32_e32 v1, 7, v0
	v_lshlrev_b32_e32 v0, 8, v1
	global_atomic_add v0, v0, v230, s[82:83] sc0
	s_waitcnt vmcnt(0)
	v_add_u32_e32 v2, 0x0, v0
	v_add_u32_e32 v4, 0x0, v0
	v_cmp_gt_u32_e32 vcc, 0xe8, v0
	s_nop 1
	v_cndmask_b32_e32 v2, v2, v4, vcc
	v_add_u32_e32 v4, 0x0, v0
	v_cmp_gt_u32_e32 vcc, 0xd8, v0
	s_nop 1
	v_cndmask_b32_e32 v2, v2, v4, vcc
	v_add_u32_e32 v4, 0xfffffff8, v0
	v_cmp_gt_u32_e32 vcc, 0xb8, v0
	s_nop 1
	v_cndmask_b32_e32 v2, v2, v4, vcc
	v_add_u32_e32 v4, 0xfffffff8, v0
	v_cmp_gt_u32_e32 vcc, 0xa8, v0
	s_nop 1
	v_cndmask_b32_e32 v2, v2, v4, vcc
	v_add_u32_e32 v4, 0xfffffff8, v0
	v_cmp_gt_u32_e32 vcc, 0x98, v0
	s_nop 1
	v_cndmask_b32_e32 v2, v2, v4, vcc
	v_add_u32_e32 v4, 0xfffffff8, v0
	v_cmp_gt_u32_e32 vcc, 0x78, v0
	s_nop 1
	v_cndmask_b32_e32 v2, v2, v4, vcc
	v_add_u32_e32 v4, 0xfffffff8, v0
	v_cmp_gt_u32_e32 vcc, 0x58, v0
	s_nop 1
	v_cndmask_b32_e32 v2, v2, v4, vcc
	v_add_u32_e32 v4, 0xfffffff8, v0
	v_cmp_gt_u32_e32 vcc, 0x38, v0
	s_nop 1
	v_cndmask_b32_e32 v2, v2, v4, vcc
	v_add_u32_e32 v4, 0xfffffff8, v0
	v_cmp_gt_u32_e32 vcc, 0x28, v0
	s_nop 1
	v_cndmask_b32_e32 v2, v2, v4, vcc
	v_add_u32_e32 v4, 0xb0, v0
	v_cmp_gt_u32_e32 vcc, 0x8, v0
	s_nop 1
	v_cndmask_b32_e32 v2, v2, v4, vcc
	v_cmp_gt_u32_e32 vcc, 0xf8, v0
	s_nop 1
	v_cndmask_b32_e32 v0, v0, v2, vcc
	s_nop 1
	v_cmp_lt_i32_e32 vcc, s95, v0
	s_and_saveexec_b64 s[4:5], vcc
	s_xor_b64 s[4:5], exec, s[4:5]
	v_add_u32_e32 v196, 1, v196
	s_or_saveexec_b64 s[4:5], s[4:5]
	v_mov_b32_e32 v197, 0x7d0
	s_xor_b64 exec, exec, s[4:5]
	s_cbranch_execz .LBB0_854
	v_cmp_lt_i32_e32 vcc, 31, v0
	s_and_saveexec_b64 s[10:11], vcc
	s_xor_b64 s[10:11], exec, s[10:11]
	s_cbranch_execz .LBB0_896
	v_cmp_lt_u32_e32 vcc, 47, v0
	s_and_saveexec_b64 s[12:13], vcc
	s_xor_b64 s[12:13], exec, s[12:13]
	s_cbranch_execz .LBB0_893
	s_movk_i32 s14, 0x4f
	v_cmp_lt_u32_e32 vcc, s14, v0
	s_and_saveexec_b64 s[14:15], vcc
	s_xor_b64 s[14:15], exec, s[14:15]
	s_cbranch_execz .LBB0_890
	s_movk_i32 s16, 0x6f
	v_cmp_lt_u32_e32 vcc, s16, v0
	s_and_saveexec_b64 s[16:17], vcc
	s_xor_b64 s[16:17], exec, s[16:17]
	s_cbranch_execz .LBB0_887
	s_movk_i32 s18, 0x8f
	v_cmp_lt_u32_e32 vcc, s18, v0
	s_and_saveexec_b64 s[18:19], vcc
	s_xor_b64 s[18:19], exec, s[18:19]
	s_cbranch_execz .LBB0_884
	s_movk_i32 s20, 0x9f
	v_cmp_lt_u32_e32 vcc, s20, v0
	s_and_saveexec_b64 s[20:21], vcc
	s_xor_b64 s[20:21], exec, s[20:21]
	s_cbranch_execz .LBB0_881
	s_movk_i32 s22, 0xaf
	v_cmp_lt_u32_e32 vcc, s22, v0
	s_and_saveexec_b64 s[22:23], vcc
	s_xor_b64 s[22:23], exec, s[22:23]
	s_cbranch_execz .LBB0_878
	s_movk_i32 s24, 0xb7
	v_cmp_lt_u32_e32 vcc, s24, v0
	s_and_saveexec_b64 s[24:25], vcc
	s_xor_b64 s[24:25], exec, s[24:25]
	s_cbranch_execz .LBB0_875
	s_movk_i32 s33, 0xd7
	v_cmp_lt_u32_e32 vcc, s33, v0
	s_and_saveexec_b64 s[34:35], vcc
	s_xor_b64 s[34:35], exec, s[34:35]
	s_cbranch_execz .LBB0_872
	s_movk_i32 s33, 0xe7
	v_cmp_lt_u32_e32 vcc, s33, v0
	v_lshlrev_b32_e32 v1, 4, v1
	s_and_saveexec_b64 s[44:45], vcc
	s_xor_b64 s[56:57], exec, s[44:45]
	s_movk_i32 s33, 0x668
	v_add3_u32 v197, v0, v1, s33
	s_andn2_saveexec_b64 s[56:57], s[56:57]
	s_movk_i32 s33, 0x5f8
	v_add3_u32 v197, v0, v1, s33
	s_or_b64 exec, exec, s[56:57]

.LBB0_915:
	v_add_u32_e32 v0, s3, v196
	v_and_b32_e32 v1, 7, v0
	v_lshlrev_b32_e32 v0, 8, v1
	global_atomic_add v0, v0, v230, s[82:83] sc0
	s_waitcnt vmcnt(0)
	v_add_u32_e32 v2, 0x0, v0
	v_add_u32_e32 v4, 0x0, v0
	v_cmp_gt_u32_e32 vcc, 0xe8, v0
	s_nop 1
	v_cndmask_b32_e32 v2, v2, v4, vcc
	v_add_u32_e32 v4, 0x0, v0
	v_cmp_gt_u32_e32 vcc, 0xd8, v0
	s_nop 1
	v_cndmask_b32_e32 v2, v2, v4, vcc
	v_add_u32_e32 v4, 0xfffffff8, v0
	v_cmp_gt_u32_e32 vcc, 0xb8, v0
	s_nop 1
	v_cndmask_b32_e32 v2, v2, v4, vcc
	v_add_u32_e32 v4, 0xfffffff8, v0
	v_cmp_gt_u32_e32 vcc, 0xa8, v0
	s_nop 1
	v_cndmask_b32_e32 v2, v2, v4, vcc
	v_add_u32_e32 v4, 0xfffffff8, v0
	v_cmp_gt_u32_e32 vcc, 0x98, v0
	s_nop 1
	v_cndmask_b32_e32 v2, v2, v4, vcc
	v_add_u32_e32 v4, 0xfffffff8, v0
	v_cmp_gt_u32_e32 vcc, 0x78, v0
	s_nop 1
	v_cndmask_b32_e32 v2, v2, v4, vcc
	v_add_u32_e32 v4, 0xfffffff8, v0
	v_cmp_gt_u32_e32 vcc, 0x58, v0
	s_nop 1
	v_cndmask_b32_e32 v2, v2, v4, vcc
	v_add_u32_e32 v4, 0xfffffff8, v0
	v_cmp_gt_u32_e32 vcc, 0x38, v0
	s_nop 1
	v_cndmask_b32_e32 v2, v2, v4, vcc
	v_add_u32_e32 v4, 0xfffffff8, v0
	v_cmp_gt_u32_e32 vcc, 0x28, v0
	s_nop 1
	v_cndmask_b32_e32 v2, v2, v4, vcc
	v_add_u32_e32 v4, 0xb0, v0
	v_cmp_gt_u32_e32 vcc, 0x8, v0
	s_nop 1
	v_cndmask_b32_e32 v2, v2, v4, vcc
	v_cmp_gt_u32_e32 vcc, 0xf8, v0
	s_nop 1
	v_cndmask_b32_e32 v0, v0, v2, vcc
	s_nop 1
	v_cmp_lt_i32_e32 vcc, s95, v0
	s_and_saveexec_b64 s[6:7], vcc
	s_xor_b64 s[6:7], exec, s[6:7]
	v_add_u32_e32 v196, 1, v196
	s_or_saveexec_b64 s[6:7], s[6:7]
	v_mov_b32_e32 v197, 0x7d0
	s_xor_b64 exec, exec, s[6:7]
	s_cbranch_execz .LBB0_914
	v_cmp_lt_i32_e32 vcc, 31, v0
	s_and_saveexec_b64 s[14:15], vcc
	s_xor_b64 s[14:15], exec, s[14:15]
	s_cbranch_execz .LBB0_956
	v_cmp_lt_u32_e32 vcc, 47, v0
	s_and_saveexec_b64 s[16:17], vcc
	s_xor_b64 s[16:17], exec, s[16:17]
	s_cbranch_execz .LBB0_953
	s_movk_i32 s18, 0x4f
	v_cmp_lt_u32_e32 vcc, s18, v0
	s_and_saveexec_b64 s[18:19], vcc
	s_xor_b64 s[18:19], exec, s[18:19]
	s_cbranch_execz .LBB0_950
	s_movk_i32 s20, 0x6f
	v_cmp_lt_u32_e32 vcc, s20, v0
	s_and_saveexec_b64 s[20:21], vcc
	s_xor_b64 s[20:21], exec, s[20:21]
	s_cbranch_execz .LBB0_947
	s_movk_i32 s22, 0x8f
	v_cmp_lt_u32_e32 vcc, s22, v0
	s_and_saveexec_b64 s[22:23], vcc
	s_xor_b64 s[22:23], exec, s[22:23]
	s_cbranch_execz .LBB0_944
	s_movk_i32 s24, 0x9f
	v_cmp_lt_u32_e32 vcc, s24, v0
	s_and_saveexec_b64 s[24:25], vcc
	s_xor_b64 s[24:25], exec, s[24:25]
	s_cbranch_execz .LBB0_941
	s_movk_i32 s33, 0xaf
	v_cmp_lt_u32_e32 vcc, s33, v0
	s_and_saveexec_b64 s[34:35], vcc
	s_xor_b64 s[34:35], exec, s[34:35]
	s_cbranch_execz .LBB0_938
	s_movk_i32 s33, 0xb7
	v_cmp_lt_u32_e32 vcc, s33, v0
	s_and_saveexec_b64 s[44:45], vcc
	s_xor_b64 s[56:57], exec, s[44:45]
	s_cbranch_execz .LBB0_935
	s_movk_i32 s33, 0xd7
	v_cmp_lt_u32_e32 vcc, s33, v0
	s_and_saveexec_b64 s[44:45], vcc
	s_xor_b64 s[76:77], exec, s[44:45]
	s_cbranch_execz .LBB0_932
	s_movk_i32 s33, 0xe7
	v_cmp_lt_u32_e32 vcc, s33, v0
	v_lshlrev_b32_e32 v1, 4, v1
	s_and_saveexec_b64 s[44:45], vcc
	s_xor_b64 s[66:67], exec, s[44:45]
	s_movk_i32 s33, 0x668
	v_add3_u32 v197, v0, v1, s33
	s_andn2_saveexec_b64 s[66:67], s[66:67]
	s_movk_i32 s33, 0x5f8
	v_add3_u32 v197, v0, v1, s33
	s_or_b64 exec, exec, s[66:67]
